# layer-1 FFN1-down conversion in the step-2 tail (pointer stash lanes 63/59), on top of rotated P0 loops
# speedup vs baseline: 1.0150x; 1.0135x over previous
; #define LAS __attribute__((address_space(3)))
; #define OPQ_V(x) asm volatile("" : "+v"(x))
; __device__ __forceinline__ void p0_item(const float* s0, const float* s1, int nv0, int nv1, int N, bf16* dst, int K, LAS float* scr, int lane, const float* gain  ) {
;     const int r = lane >> 4, c4 = lane & 15, hf = c4 >> 3, cc = (c4 & 7) * 4;
;     const float* src = (hf ? s1 : s0) + (size_t)r * N + cc;
;     const bool ok = cc < (hf ? nv1 : nv0);
;     f32x4 v[16];
; #pragma unroll
;     for (int i = 0; i < 16; ++i) v[i] = ok ? __builtin_nontemporal_load((const f32x4*)(src + (size_t)(4 * i) * N)) : (f32x4){0.f, 0.f, 0.f, 0.f};
; #pragma unroll
;     for (int i = 0; i < 16; ++i) { const float gk = gain ? gain[4 * i + r] : 1.f; LAS float* d = scr + (4 * i + r) * 65 + 4 * c4; d[0] = v[i].x * gk; d[1] = v[i].y * gk; d[2] = v[i].z * gk; d[3] = v[i].w * gk; }
;     const int c = lane & 7;
; #pragma unroll
;     for (int j = 0; j < 8; ++j) {
;         const int n = (lane >> 3) + 8 * j; const LAS float* s = scr + (8 * c) * 65 + n;
; __global__ void __launch_bounds__(512, 2) fwd_megakernel(Args args) {
;     ...
;     {
;         unsigned char* ws = args.ws;
;         int tid_ = threadIdx.x; OPQ_V(tid_); const int tid = tid_, lane = tid & 63, wave = __builtin_amdgcn_readfirstlane(tid >> 6);
;         const int gw = bx * 8 + wave, NGW = G * 8;
;         LAS float* scr = (LAS float*)((LAS unsigned char*)lds + wave * 16640);
; #pragma unroll 1
;         for (int l = 0; l < NLAYER; ++l) {
;             unsigned char* lw = ws + (size_t)l * LW_BYTES;
;             conv_set(CV_ARGS(args), ws, l, l == 0 ? (CV_GU1 | CV_D1 | CV_WIN) : CV_D1, scr, gw, NGW, lane);
.LBB0_9:
	v_mov_b32_e32 v1, v202
	s_lshl_b32 s4, s58, 3
	v_readfirstlane_b32 s2, v1
	s_ashr_i32 s3, s2, 6
	s_add_i32 s30, s3, s4
	s_mul_i32 s4, s3, 0x4100
	v_lshlrev_b32_e32 v3, 4, v1
	s_add_i32 s6, s4, 0
	v_and_b32_e32 v3, 0xf0, v3
	v_bfe_u32 v70, v1, 4, 2
	v_add_u32_e32 v67, s6, v3
	s_movk_i32 s8, 0x104
	v_mov_b32_e32 v3, 0x410
	v_mad_u32_u24 v71, v70, s8, v3
	v_mov_b32_e32 v3, 0x820
	v_mad_u32_u24 v113, v70, s8, v3
	v_mov_b32_e32 v3, 0xc30
	s_load_dwordx16 s[12:27], s[0:1], 0x8
	v_mad_u32_u24 v118, v70, s8, v3
	v_mov_b32_e32 v3, 0x1040
	s_waitcnt lgkmcnt(0)
	v_writelane_b32 v255, s20, 63
	v_writelane_b32 v255, s21, 59
	s_lshl_b32 s34, s72, 3
	v_mad_u32_u24 v119, v70, s8, v3
	v_mov_b32_e32 v3, 0x1450
	s_cmpk_lt_i32 s30, 0xac0
	v_mad_u32_u24 v120, v70, s8, v3
	v_mov_b32_e32 v3, 0x1860
	s_cselect_b64 s[46:47], -1, 0
	s_lshl_b32 s59, s58, 9
	v_mad_u32_u24 v121, v70, s8, v3
	v_mov_b32_e32 v3, 0x1c70
	s_cmpk_lt_i32 s30, 0x1580
	v_mad_u32_u24 v122, v70, s8, v3
	v_mov_b32_e32 v3, 0x2080
	s_cselect_b64 s[48:49], -1, 0
	s_cmp_lg_u64 s[14:15], 0
	v_mad_u32_u24 v123, v70, s8, v3
	v_mov_b32_e32 v3, 0x2490
	s_cselect_b64 s[50:51], -1, 0
	v_mad_u32_u24 v124, v70, s8, v3
	v_mov_b32_e32 v3, 0x28a0
	v_lshlrev_b32_e32 v4, 3, v1
	s_cmpk_lt_i32 s30, 0x1180
	v_mad_u32_u24 v125, v70, s8, v3
	v_bfe_u32 v3, v1, 3, 3
	v_and_b32_e32 v4, 56, v4
	s_cselect_b64 s[52:53], -1, 0
	s_cmp_lg_u64 s[22:23], 0
	s_load_dwordx8 s[36:43], s[0:1], 0x80
	v_add_u32_e32 v68, s59, v1
	v_mul_u32_u24_e32 v5, 0x104, v4
	v_lshlrev_b32_e32 v6, 2, v3
	s_cselect_b64 s[54:55], -1, 0
	s_lshl_b32 s35, s58, 8
	s_lshl_b32 s3, s3, 5
	s_movk_i32 s7, 0x1580
	v_add3_u32 v126, s6, v5, v6
	v_mov_b32_e32 v5, 0x2b000
	s_add_i32 s35, s35, s3
	s_lshl_b32 s3, s72, 8
	s_andn2_b32 s2, s2, 63
	v_ashrrev_i32_e32 v69, 31, v68
	v_mad_u32_u24 v24, v3, s7, v5
	v_mov_b32_e32 v5, 0x35c00
	v_writelane_b32 v253, s3, 0
	s_add_i32 s59, s59, s2
	v_lshl_add_u64 v[32:33], v[68:69], 1, s[56:57]
	s_mov_b64 s[2:3], 0xb610000
	v_mad_u32_u24 v26, v3, s7, v5
	v_mov_b32_e32 v5, 0x40800
	v_lshl_add_u64 v[74:75], v[32:33], 0, s[2:3]
	v_lshlrev_b64 v[32:33], 2, v[68:69]
	v_and_b32_e32 v69, 63, v1
	v_mul_u32_u24_e32 v2, 0x1580, v70
	v_lshlrev_b32_e32 v6, 11, v3
	v_mad_u32_u24 v28, v3, s7, v5
	v_mov_b32_e32 v5, 0x4b400
	s_lshl_b32 s76, s72, 9
	v_lshlrev_b32_e32 v66, 2, v69
	s_mov_b32 s31, 0x20000
	s_movk_i32 s4, 0x2700
	v_or_b32_e32 v8, 0x4000, v6
	v_or_b32_e32 v10, 0x8000, v6
	v_or_b32_e32 v12, 0xc000, v6
	v_or_b32_e32 v14, 0x10000, v6
	v_or_b32_e32 v16, 0x14000, v6
	v_or_b32_e32 v18, 0x18000, v6
	v_or_b32_e32 v20, 0x1c000, v6
	v_lshlrev_b32_e32 v22, 11, v70
	v_mad_u32_u24 v30, v3, s7, v5
	v_and_b32_e32 v127, 15, v1
	s_ashr_i32 s77, s76, 31
	s_waitcnt lgkmcnt(0)
	v_lshl_add_u64 v[76:77], s[40:41], 0, v[32:33]
	v_writelane_b32 v253, s56, 1
	s_mov_b64 s[2:3], 0xb650800
	v_lshlrev_b32_e32 v72, 2, v2
	v_lshl_add_u64 v[32:33], s[56:57], 0, v[32:33]
	v_lshlrev_b32_e32 v80, 1, v4
	v_mul_u32_u24_e32 v2, 0x2230, v70
	v_mul_u32_u24_e32 v4, 0x1580, v3
	v_and_b32_e32 v112, 28, v66
	s_movk_i32 s60, 0xac00
	s_movk_i32 s62, 0xcc00
	s_movk_i32 s64, 0xdc00
	s_movk_i32 s66, 0xec00
	s_movk_i32 s68, 0xfc00
	s_movk_i32 s70, 0xff00
	v_cmp_gt_i32_e64 s[10:11], s31, v68
	v_cmp_gt_i32_e64 s[4:5], s4, v68
	v_mov_b32_e32 v73, 0
	s_mov_b32 s33, 0x2b000
	v_lshl_add_u32 v128, v127, 4, s6
	v_writelane_b32 v253, s57, 2
	v_lshl_add_u64 v[78:79], v[32:33], 0, s[2:3]
	s_mov_b32 s84, 0x15000
	s_mov_b32 s85, 0x40000
	v_lshlrev_b32_e32 v82, 1, v6
	v_lshlrev_b32_e32 v84, 1, v8
	v_lshlrev_b32_e32 v86, 1, v10
	v_lshlrev_b32_e32 v88, 1, v12
	v_lshlrev_b32_e32 v90, 1, v14
	v_lshlrev_b32_e32 v92, 1, v16
	v_lshlrev_b32_e32 v94, 1, v18
	v_lshlrev_b32_e32 v96, 1, v20
	v_lshlrev_b32_e32 v98, 2, v22
	v_cndmask_b32_e64 v129, 0, 1, s[50:51]
	v_lshlrev_b32_e32 v100, 1, v4
	v_lshlrev_b32_e32 v102, 1, v24
	v_lshlrev_b32_e32 v104, 1, v26
	v_lshlrev_b32_e32 v106, 1, v28
	v_lshlrev_b32_e32 v108, 1, v30
	v_lshlrev_b32_e32 v110, 2, v2
	v_lshlrev_b32_e32 v114, 2, v112
	v_mul_u32_u24_e32 v130, 0x104, v70
	v_and_b32_e32 v131, 32, v66
	v_and_b32_e32 v132, 0x7f, v1
	s_mov_b32 s44, s45
	s_mov_b64 s[80:81], 0
	v_cmp_gt_u32_e64 s[6:7], 8, v127
	s_lshl_b64 s[40:41], s[76:77], 1
	s_lshl_b64 s[56:57], s[76:77], 2
	s_mov_b64 s[74:75], -1
	s_mov_b32 s61, -1
	s_mov_b32 s63, -1
	s_mov_b32 s65, -1
	s_mov_b32 s67, -1
	s_mov_b32 s69, -1
	s_mov_b32 s71, -1
	s_branch .LBB0_11

; #define LAS __attribute__((address_space(3)))
; __device__ __forceinline__ void p0_matrix(int type  , const float* W0, const float* W1, int K, int Nsrc, int Ndst, bf16* dst, LAS float* scr, int gw, int NGW, int lane, const float* gain) {
;     const int nruns = Ndst >> 6, nitems = (K >> 6) * nruns;
;     for (int it = gw; it < nitems; it += NGW) {
;         const int kb = it / nruns, nb = it - kb * nruns, n0 = nb * 64, k0 = kb * 64;
;         const float* src = W0; int c0 = n0, c1 = n0 + 32, nv0 = 32, nv1 = 32;
;         if (type == 1) { const int tile = n0 >> 8, r = n0 & 255; src = r < 128 ? W0 : W1; c0 = tile * 128 + (r & 127); c1 = c0 + 32; }
;         else if (type == 2) { c0 = win_src_col(n0, nv0); c1 = win_src_col(n0 + 32, nv1); }
;         const float* rowp = src + (size_t)k0 * Nsrc;
;         p0_item(rowp + c0, rowp + c1, nv0, nv1, Nsrc, dst + (size_t)n0 * K + k0, K, scr, lane, gain ? gain + k0 : nullptr);
; __device__ __forceinline__ void conv_set(const CvPtrs args, unsigned char* ws, int l, unsigned mask, LAS float* scr, int gw, int NGW, int lane) {
;     ...
;     if (mask & CV_D2) p0_matrix(0, args.in[26] + (size_t)l * FF * D, nullptr, FF, D, D, (bf16*)(lw + LW_D2), scr, gw, NGW, lane, nullptr);
.LBB0_1602:
	s_bitcmp0_b32 s19, 7
	s_mov_b32 s25, 0x15000
	s_cbranch_scc1 .LBB0_1606
	s_cmpk_gt_i32 s3, 0xabf
	s_cbranch_scc1 .LBB0_1606
	v_lshlrev_b32_e32 v4, 4, v90
	s_mul_i32 s0, s20, 0x2b00000
	v_and_b32_e32 v4, 0xf0, v4
	s_add_u32 s2, s52, s0
	v_add_u32_e32 v7, s22, v4
	v_lshlrev_b32_e32 v4, 3, v90
	s_addc_u32 s6, s53, 0
	v_lshrrev_b32_e32 v9, 3, v90
	v_and_b32_e32 v4, 56, v4
	s_add_u32 s7, s4, 0x9e80000
	v_lshrrev_b32_e32 v3, 4, v90
	v_lshlrev_b32_e32 v5, 2, v90
	v_mul_u32_u24_e32 v6, 0x104, v4
	v_lshlrev_b32_e32 v8, 2, v9
	s_movk_i32 s0, 0x1580
	v_mov_b32_e32 v10, 0x35c00
	s_addc_u32 s10, s5, 0
	v_and_b32_e32 v2, 28, v5
	v_lshlrev_b32_e32 v0, 11, v3
	v_mul_u32_u24_e32 v3, 0x104, v3
	v_add3_u32 v76, s22, v6, v8
	v_mul_u32_u24_e32 v6, 0x1580, v9
	v_mad_u32_u24 v8, v9, s0, v252
	v_mad_u32_u24 v10, v9, s0, v10
	v_mad_u32_u24 v12, v9, s0, v236
	v_mad_u32_u24 v14, v9, s0, v237
	s_lshl_b32 s0, s21, 9
	v_and_b32_e32 v77, 32, v5
	s_lshl_b32 s11, s3, 6
	s_sub_i32 s12, s76, s0
	v_lshlrev_b32_e32 v0, 2, v0
	v_lshlrev_b32_e32 v62, 2, v2
	v_add_u32_e32 v78, v7, v3
	v_lshlrev_b32_e32 v64, 1, v4
	v_lshlrev_b32_e32 v66, 1, v6
	v_lshlrev_b32_e32 v68, 1, v8
	v_lshlrev_b32_e32 v70, 1, v10
	v_lshlrev_b32_e32 v72, 1, v12
	v_lshlrev_b32_e32 v74, 1, v14
	s_mov_b32 s13, s3
	s_mov_b32 s26, 0x2b000
	s_mov_b32 s27, 0x48000
	s_mov_b32 s28, 0x50000
	s_mov_b32 s36, 0x58000
	s_mov_b32 s37, 0x60000
	s_mov_b32 s64, 0x68000
	s_mov_b32 s65, 0x70000
	s_mov_b32 s66, 0x78000
	v_readlane_b32 s0, v255, 62
	s_nop 3
	s_cmp_lg_u32 s0, 1
	s_cbranch_scc1 .Ld1ovr_skip
	v_readlane_b32 s2, v255, 63
	v_readlane_b32 s6, v255, 59
	s_nop 3
	s_mul_i32 s0, s20, 0x2b00000
	s_add_u32 s2, s2, s0
	s_addc_u32 s6, s6, 0
	s_add_u32 s7, s4, 0x2b00000
	s_addc_u32 s10, s5, 0
